# M1: on leaving the main loop each wave touches 3 KB of the pooling code (24 KB in all) so the once-executed pooling pass fetches its instructions from L2
# speedup vs baseline: 1.0026x; 1.0022x over previous
; __device__ __forceinline__ void m1_phase(const Params& p, unsigned char* ldsg, int G) {
;     ...
;     for (int r = blockIdx.x; r < NCH * NH / 2; r += G) {
;         const int c = r >> 1, h = 2 * (r & 1) + half, u = c * 4 + h, t0 = c * CL;
;         if (hw == 0) {
;     ...
;         __syncthreads();
;     }
;     bf16* MIX = (bf16*)(ws + WS_MIX);
;     for (int rb = blockIdx.x; rb < S / 64; rb += G) {
.Lm1pf_skip_1:
	s_cmpk_gt_i32 s82, 0x1ff
	s_barrier
	s_cbranch_scc1 .LBB0_648
	s_branch .LBB0_611
.Lm1_poolwarm:
	s_getpc_b64 s[98:99]
.Lm1_poolwarm_pc:
	s_add_u32 s98, s98, .LBB0_648-.Lm1_poolwarm_pc
	s_addc_u32 s99, s99, 0
	v_lshrrev_b32_e32 v200, 6, v152
	v_mul_u32_u24_e32 v200, 0xc00, v200
	v_and_b32_e32 v201, 63, v152
	v_lshl_add_u32 v200, v201, 4, v200
	v_mov_b32_e32 v201, 0
	v_lshl_add_u64 v[200:201], s[98:99], 0, v[200:201]
	global_load_dwordx4 v[188:191], v[200:201], off
	global_load_dwordx4 v[192:195], v[200:201], off offset:1024
	global_load_dwordx4 v[196:199], v[200:201], off offset:2048
	s_branch .Lm1pf_skip_1
